# gate/up GEMM loop: B-fragment ds_read addresses from one per-unit base register with immediate offsets (four VALU adds per iteration removed)
# speedup vs baseline: 1.0151x; 1.0033x over previous
;     DI size_t a_row(int pm) const { return (size_t)pm * 256; }
; #define PG8_STAGE(bufoff, gbase, voff) do { _Pragma("unroll") for (int _i = 0; _i < 2; ++_i) \
;         __builtin_amdgcn_global_load_lds((const unsigned*)((const char*)(gbase) + (voff)[_i]), (LAS unsigned*)(lds + (bufoff) + ldsw + _i * 8192), 16, 0, 0); } while (0)
; #define PG8_LDA(dst, b, h) do { _Pragma("unroll") for (int m = 0; m < 4; ++m) _Pragma("unroll") for (int k = 0; k < 2; ++k) dst[m][k] = *(const LAS bf16x8*)(lds + PG8_SA(b, h) + aoff + m * 2048 + k * 1024); } while (0)
; #define PG8_LDB(dst, b, h) do { _Pragma("unroll") for (int n = 0; n < 2; ++n) _Pragma("unroll") for (int k = 0; k < 2; ++k) dst[n][k] = *(const LAS bf16x8*)(lds + PG8_SB(b, h) + boff + n * 2048 + k * 1024); } while (0)
; #define PG8_WAIT_V(n) asm volatile("s_waitcnt vmcnt(" #n ")" ::: "memory")
; #define PG8_WAIT_L(n) asm volatile("s_waitcnt lgkmcnt(" #n ")" ::: "memory")
; #define PG8_BAR __builtin_amdgcn_s_barrier()
; #define PG8_SCHED __builtin_amdgcn_sched_barrier(0)
; template <class Epi, class Sched, bool ALIGN_EPI>
; DI void gemm_phase(LAS unsigned char* lds, const Gemm g, const Sched& S, const Epi& E) {
;     ...
;         const char* nA = has_next ? (const char*)g.A + S.a_row(nxt.pm) * rowb + (size_t)nxt.kt0 * kstep : cA; const char* nB = has_next ? (const char*)g.Bt + (size_t)nxt.pn * 2 * hstep + (size_t)nxt.kt0 * kstep : cB;
;         const int nt = cur.nkt;
;         for (int t = 0; t < nt; t += 2) {
;             const bool last = (t == nt - 2);
;             const char* a1 = cA + (size_t)(t + 1) * kstep;
;             const char* a2 = last ? nA : cA + (size_t)(t + 2) * kstep; const char* b2 = last ? nB : cB + (size_t)(t + 2) * kstep;
;             const char* a3 = a2 + kstep; const char* b3 = b2 + kstep;
;             PG8_LDB(B0, 0, 0); PG8_LDB(B1, 0, 1); PG8_SCHED; PG8_LDA(At, 0, 0); PG8_STAGE(PG8_SA(1, 1), a1 + hstep, voffA);
;             PG8_WAIT_V(8); PG8_WAIT_L(0); PG8_BAR; PG8_MMA(0, 0, At, B0); PG8_MMA(0, 1, At, B1); PG8_BAR; PG8_SCHED;
;     ...
; #pragma unroll
;         for (int a = 0; a < 2; ++a)
; #pragma unroll
;             for (int b = 0; b < 2; ++b)
; #pragma unroll
;                 for (int m = 0; m < 4; ++m)
; #pragma unroll
;                     for (int n = 0; n < 2; ++n) acc[a][b][m][n] = (f32x4){0.f, 0.f, 0.f, 0.f};
;         cur = nxt; cA = nA; cB = nB; ++ui;
.LBB0_825:
	s_ashr_i32 s23, s22, 31
	s_lshl_b64 s[26:27], s[22:23], 19
	v_readlane_b32 s23, v253, 12
	s_add_u32 s26, s23, s26
	v_readlane_b32 s23, v253, 13
	s_addc_u32 s27, s23, s27
	s_and_b64 s[34:35], s[34:35], exec
	s_cselect_b32 s23, s27, s31
	s_cselect_b32 s29, s26, s30
	s_add_u32 s0, s0, 0x40080
	s_addc_u32 s1, s1, 0
	s_add_u32 s43, s30, 0x100
	v_mov_b64_e32 v[0:1], 0
	s_addc_u32 s44, s31, 0
	s_mov_b32 s45, -2
	v_mov_b64_e32 v[2:3], 0
	v_mov_b64_e32 v[80:81], 0
	v_mov_b64_e32 v[82:83], 0
	v_mov_b64_e32 v[8:9], 0
	v_mov_b64_e32 v[10:11], 0
	v_mov_b64_e32 v[88:89], 0
	v_mov_b64_e32 v[90:91], 0
	v_mov_b64_e32 v[16:17], 0
	v_mov_b64_e32 v[18:19], 0
	v_mov_b64_e32 v[96:97], 0
	v_mov_b64_e32 v[98:99], 0
	v_mov_b64_e32 v[24:25], 0
	v_mov_b64_e32 v[26:27], 0
	v_mov_b64_e32 v[104:105], 0
	v_mov_b64_e32 v[106:107], 0
	v_mov_b64_e32 v[4:5], 0
	v_mov_b64_e32 v[6:7], 0
	v_mov_b64_e32 v[84:85], 0
	v_mov_b64_e32 v[86:87], 0
	v_mov_b64_e32 v[12:13], 0
	v_mov_b64_e32 v[14:15], 0
	v_mov_b64_e32 v[92:93], 0
	v_mov_b64_e32 v[94:95], 0
	v_mov_b64_e32 v[20:21], 0
	v_mov_b64_e32 v[22:23], 0
	v_mov_b64_e32 v[100:101], 0
	v_mov_b64_e32 v[102:103], 0
	v_mov_b64_e32 v[28:29], 0
	v_mov_b64_e32 v[30:31], 0
	v_mov_b64_e32 v[108:109], 0
	v_mov_b64_e32 v[110:111], 0
	v_mov_b64_e32 v[32:33], 0
	v_mov_b64_e32 v[34:35], 0
	v_mov_b64_e32 v[112:113], 0
	v_mov_b64_e32 v[114:115], 0
	v_mov_b64_e32 v[40:41], 0
	v_mov_b64_e32 v[42:43], 0
	v_mov_b64_e32 v[120:121], 0
	v_mov_b64_e32 v[122:123], 0
	v_mov_b64_e32 v[64:65], 0
	v_mov_b64_e32 v[66:67], 0
	v_mov_b64_e32 v[144:145], 0
	v_mov_b64_e32 v[146:147], 0
	v_mov_b64_e32 v[72:73], 0
	v_mov_b64_e32 v[74:75], 0
	v_mov_b64_e32 v[152:153], 0
	v_mov_b64_e32 v[154:155], 0
	v_mov_b64_e32 v[36:37], 0
	v_mov_b64_e32 v[38:39], 0
	v_mov_b64_e32 v[116:117], 0
	v_mov_b64_e32 v[118:119], 0
	s_waitcnt vmcnt(0)
	v_mov_b64_e32 v[60:61], 0
	v_mov_b64_e32 v[62:63], 0
	v_mov_b64_e32 v[140:141], 0
	v_mov_b64_e32 v[142:143], 0
	v_mov_b64_e32 v[68:69], 0
	v_mov_b64_e32 v[70:71], 0
	v_mov_b64_e32 v[148:149], 0
	v_mov_b64_e32 v[150:151], 0
	v_mov_b64_e32 v[76:77], 0
	v_mov_b64_e32 v[78:79], 0
	v_mov_b64_e32 v[156:157], 0
	v_mov_b64_e32 v[158:159], 0
	v_add_u32_e32 v206, 0x10000, v241
.LBB0_826:
	s_add_u32 s30, s0, 0xfffc0080
	s_addc_u32 s31, s1, -1
	s_add_i32 s46, 0, 0x10000
	s_cmp_eq_u32 s45, 12
	s_cselect_b32 s35, s25, s31
	s_cselect_b32 s34, s24, s30
	s_cselect_b32 s31, s23, s44
	s_cselect_b32 s30, s29, s43
	s_add_i32 s52, 0, 0x14000
	ds_read_b128 v[44:47], v206
	ds_read_b128 v[48:51], v206 offset:1024
	ds_read_b128 v[52:55], v206 offset:2048
	ds_read_b128 v[56:59], v206 offset:3072
	ds_read_b128 v[124:127], v206 offset:16384
	ds_read_b128 v[128:131], v206 offset:17408
	ds_read_b128 v[132:135], v206 offset:18432
	ds_read_b128 v[136:139], v206 offset:19456
	s_add_i32 m0, s93, 0xc000
	ds_read_b128 v[160:163], v245
	ds_read_b128 v[164:167], v245 offset:1024
	ds_read_b128 v[182:185], v245 offset:2048
	ds_read_b128 v[186:189], v245 offset:3072
	ds_read_b128 v[190:193], v245 offset:4096
	ds_read_b128 v[194:197], v245 offset:5120
	ds_read_b128 v[198:201], v245 offset:6144
	ds_read_b128 v[202:205], v245 offset:7168
	global_load_lds_dwordx4 v178, s[0:1]
	s_add_i32 m0, s93, 0xe000
	s_nop 0
	global_load_lds_dwordx4 v180, s[0:1]
	s_waitcnt vmcnt(8)
	s_waitcnt lgkmcnt(0)
	s_barrier
	s_setprio 1
	s_waitcnt lgkmcnt(0)
	v_mfma_f32_16x16x32_bf16 v[156:159], v[44:47], v[160:163], v[156:159]
	v_mfma_f32_16x16x32_bf16 v[76:79], v[52:55], v[160:163], v[76:79]
	v_mfma_f32_16x16x32_bf16 v[148:151], v[44:47], v[182:185], v[148:151]
	v_mfma_f32_16x16x32_bf16 v[68:71], v[52:55], v[182:185], v[68:71]
	v_mfma_f32_16x16x32_bf16 v[140:143], v[44:47], v[190:193], v[140:143]
	v_mfma_f32_16x16x32_bf16 v[60:63], v[52:55], v[190:193], v[60:63]
	v_mfma_f32_16x16x32_bf16 v[116:119], v[44:47], v[198:201], v[116:119]
	v_mfma_f32_16x16x32_bf16 v[36:39], v[52:55], v[198:201], v[36:39]
	v_mfma_f32_16x16x32_bf16 v[156:159], v[48:51], v[164:167], v[156:159]
	v_mfma_f32_16x16x32_bf16 v[76:79], v[56:59], v[164:167], v[76:79]
	v_mfma_f32_16x16x32_bf16 v[148:151], v[48:51], v[186:189], v[148:151]
	v_mfma_f32_16x16x32_bf16 v[68:71], v[56:59], v[186:189], v[68:71]
	v_mfma_f32_16x16x32_bf16 v[140:143], v[48:51], v[194:197], v[140:143]
	v_mfma_f32_16x16x32_bf16 v[60:63], v[56:59], v[194:197], v[60:63]
	v_mfma_f32_16x16x32_bf16 v[116:119], v[48:51], v[202:205], v[116:119]
	v_mfma_f32_16x16x32_bf16 v[36:39], v[56:59], v[202:205], v[36:39]
	s_setprio 0
	s_setprio 1
	v_mfma_f32_16x16x32_bf16 v[152:155], v[124:127], v[160:163], v[152:155]
	v_mfma_f32_16x16x32_bf16 v[72:75], v[132:135], v[160:163], v[72:75]
	v_mfma_f32_16x16x32_bf16 v[144:147], v[124:127], v[182:185], v[144:147]
	v_mfma_f32_16x16x32_bf16 v[64:67], v[132:135], v[182:185], v[64:67]
	v_mfma_f32_16x16x32_bf16 v[120:123], v[124:127], v[190:193], v[120:123]
	v_mfma_f32_16x16x32_bf16 v[40:43], v[132:135], v[190:193], v[40:43]
	v_mfma_f32_16x16x32_bf16 v[112:115], v[124:127], v[198:201], v[112:115]
	v_mfma_f32_16x16x32_bf16 v[32:35], v[132:135], v[198:201], v[32:35]
	v_mfma_f32_16x16x32_bf16 v[152:155], v[128:131], v[164:167], v[152:155]
	v_mfma_f32_16x16x32_bf16 v[72:75], v[136:139], v[164:167], v[72:75]
	v_mfma_f32_16x16x32_bf16 v[144:147], v[128:131], v[186:189], v[144:147]
	v_mfma_f32_16x16x32_bf16 v[64:67], v[136:139], v[186:189], v[64:67]
	v_mfma_f32_16x16x32_bf16 v[120:123], v[128:131], v[194:197], v[120:123]
	v_mfma_f32_16x16x32_bf16 v[40:43], v[136:139], v[194:197], v[40:43]
	v_mfma_f32_16x16x32_bf16 v[112:115], v[128:131], v[202:205], v[112:115]
	v_mfma_f32_16x16x32_bf16 v[32:35], v[136:139], v[202:205], v[32:35]
	s_setprio 0
	s_barrier
; #define PG8_STAGE(bufoff, gbase, voff) do { _Pragma("unroll") for (int _i = 0; _i < 2; ++_i) \
;         __builtin_amdgcn_global_load_lds((const unsigned*)((const char*)(gbase) + (voff)[_i]), (LAS unsigned*)(lds + (bufoff) + ldsw + _i * 8192), 16, 0, 0); } while (0)
; #define PG8_LDA(dst, b, h) do { _Pragma("unroll") for (int m = 0; m < 4; ++m) _Pragma("unroll") for (int k = 0; k < 2; ++k) dst[m][k] = *(const LAS bf16x8*)(lds + PG8_SA(b, h) + aoff + m * 2048 + k * 1024); } while (0)
; #define PG8_LDB(dst, b, h) do { _Pragma("unroll") for (int n = 0; n < 2; ++n) _Pragma("unroll") for (int k = 0; k < 2; ++k) dst[n][k] = *(const LAS bf16x8*)(lds + PG8_SB(b, h) + boff + n * 2048 + k * 1024); } while (0)
; #define PG8_MMA(ai, bj, At, Bt) do { __builtin_amdgcn_s_setprio(1); _Pragma("unroll") for (int m = 0; m < 4; ++m) _Pragma("unroll") for (int n = 0; n < 2; ++n) _Pragma("unroll") for (int k = 0; k < 2; ++k) \
;         acc[ai][bj][m][n] = __builtin_amdgcn_mfma_f32_16x16x32_bf16(Bt[n][k], At[m][k], acc[ai][bj][m][n], 0, 0, 0); __builtin_amdgcn_s_setprio(0); } while (0)
; #define PG8_WAIT_V(n) asm volatile("s_waitcnt vmcnt(" #n ")" ::: "memory")
; #define PG8_WAIT_L(n) asm volatile("s_waitcnt lgkmcnt(" #n ")" ::: "memory")
; #define PG8_BAR __builtin_amdgcn_s_barrier()
; #define PG8_SCHED __builtin_amdgcn_sched_barrier(0)
; template <class Epi, class Sched, bool ALIGN_EPI>
; DI void gemm_phase(LAS unsigned char* lds, const Gemm g, const Sched& S, const Epi& E) {
;     ...
;             PG8_LDA(At, 0, 1); PG8_STAGE(PG8_SB(0, 0), b2, voffA); PG8_STAGE(PG8_SB(0, 1), b2 + hstep, voffA); PG8_STAGE(PG8_SA(0, 0), a2, voffA);
;             PG8_WAIT_V(8); PG8_WAIT_L(0); PG8_BAR; PG8_MMA(1, 0, At, B0); PG8_MMA(1, 1, At, B1); PG8_BAR; PG8_SCHED;
;             PG8_LDB(B0, 1, 0); PG8_LDB(B1, 1, 1); PG8_SCHED; PG8_LDA(At, 1, 0); PG8_STAGE(PG8_SA(0, 1), a2 + hstep, voffA);
;             PG8_WAIT_V(8); PG8_WAIT_L(0); PG8_BAR; PG8_MMA(0, 0, At, B0); PG8_MMA(0, 1, At, B1); PG8_BAR; PG8_SCHED;
	s_add_i32 s46, s46, s92
	s_add_u32 s94, s30, s2
	s_addc_u32 s95, s31, s3
	s_add_u32 s96, s34, s2
	s_addc_u32 s97, s35, s3
	s_mov_b32 m0, s46
	ds_read_b128 v[160:163], v245 offset:16384
	ds_read_b128 v[164:167], v245 offset:17408
	ds_read_b128 v[182:185], v245 offset:18432
	ds_read_b128 v[186:189], v245 offset:19456
	ds_read_b128 v[190:193], v245 offset:20480
	ds_read_b128 v[194:197], v245 offset:21504
	ds_read_b128 v[198:201], v245 offset:22528
	ds_read_b128 v[202:205], v245 offset:23552
	global_load_lds_dwordx4 v174, s[30:31]
	s_add_i32 m0, s46, 0x2000
	s_add_u32 s46, s30, 0x40000
	s_addc_u32 s47, s31, 0
	s_add_i32 s52, s52, s92
	global_load_lds_dwordx4 v176, s[30:31]
	s_mov_b32 m0, s52
	s_nop 0
	global_load_lds_dwordx4 v174, s[46:47]
	s_add_i32 m0, s52, 0x2000
	s_nop 0
	global_load_lds_dwordx4 v176, s[46:47]
	s_mov_b32 m0, s93
	s_nop 0
	global_load_lds_dwordx4 v174, s[34:35]
	s_mov_b32 m0, s86
	s_nop 0
	global_load_lds_dwordx4 v176, s[34:35]
	s_waitcnt vmcnt(8)
	s_waitcnt lgkmcnt(0)
	s_barrier
	s_setprio 1
	s_waitcnt lgkmcnt(0)
	v_mfma_f32_16x16x32_bf16 v[108:111], v[44:47], v[160:163], v[108:111]
	v_mfma_f32_16x16x32_bf16 v[28:31], v[52:55], v[160:163], v[28:31]
	v_mfma_f32_16x16x32_bf16 v[100:103], v[44:47], v[182:185], v[100:103]
	v_mfma_f32_16x16x32_bf16 v[20:23], v[52:55], v[182:185], v[20:23]
	v_mfma_f32_16x16x32_bf16 v[92:95], v[44:47], v[190:193], v[92:95]
	v_mfma_f32_16x16x32_bf16 v[12:15], v[52:55], v[190:193], v[12:15]
	v_mfma_f32_16x16x32_bf16 v[4:7], v[52:55], v[198:201], v[4:7]
	v_mfma_f32_16x16x32_bf16 v[108:111], v[48:51], v[164:167], v[108:111]
	v_mfma_f32_16x16x32_bf16 v[28:31], v[56:59], v[164:167], v[28:31]
	v_mfma_f32_16x16x32_bf16 v[100:103], v[48:51], v[186:189], v[100:103]
	v_mfma_f32_16x16x32_bf16 v[20:23], v[56:59], v[186:189], v[20:23]
	v_mfma_f32_16x16x32_bf16 v[92:95], v[48:51], v[194:197], v[92:95]
	v_mfma_f32_16x16x32_bf16 v[12:15], v[56:59], v[194:197], v[12:15]
	v_mfma_f32_16x16x32_bf16 v[44:47], v[44:47], v[198:201], v[84:87]
	v_mfma_f32_16x16x32_bf16 v[4:7], v[56:59], v[202:205], v[4:7]
	v_mfma_f32_16x16x32_bf16 v[44:47], v[48:51], v[202:205], v[44:47]
	s_setprio 0
	s_setprio 1
	v_mfma_f32_16x16x32_bf16 v[24:27], v[132:135], v[160:163], v[24:27]
	v_mfma_f32_16x16x32_bf16 v[16:19], v[132:135], v[182:185], v[16:19]
	v_mfma_f32_16x16x32_bf16 v[8:11], v[132:135], v[190:193], v[8:11]
	v_mfma_f32_16x16x32_bf16 v[80:83], v[124:127], v[198:201], v[80:83]
	v_mfma_f32_16x16x32_bf16 v[0:3], v[132:135], v[198:201], v[0:3]
	v_mfma_f32_16x16x32_bf16 v[48:51], v[124:127], v[160:163], v[104:107]
	v_mfma_f32_16x16x32_bf16 v[24:27], v[136:139], v[164:167], v[24:27]
	v_mfma_f32_16x16x32_bf16 v[52:55], v[124:127], v[182:185], v[96:99]
	v_mfma_f32_16x16x32_bf16 v[16:19], v[136:139], v[186:189], v[16:19]
	v_mfma_f32_16x16x32_bf16 v[56:59], v[124:127], v[190:193], v[88:91]
	v_mfma_f32_16x16x32_bf16 v[8:11], v[136:139], v[194:197], v[8:11]
	v_mfma_f32_16x16x32_bf16 v[80:83], v[128:131], v[202:205], v[80:83]
	v_mfma_f32_16x16x32_bf16 v[0:3], v[136:139], v[202:205], v[0:3]
	v_mfma_f32_16x16x32_bf16 v[48:51], v[128:131], v[164:167], v[48:51]
	v_mfma_f32_16x16x32_bf16 v[52:55], v[128:131], v[186:189], v[52:55]
	v_mfma_f32_16x16x32_bf16 v[56:59], v[128:131], v[194:197], v[56:59]
	s_setprio 0
	s_barrier
	s_add_i32 s46, 0, 0x18000
	s_add_i32 s47, 0, 0x1c000
	ds_read_b128 v[84:87], v206 offset:32768
	ds_read_b128 v[88:91], v206 offset:33792
	ds_read_b128 v[96:99], v206 offset:34816
	ds_read_b128 v[104:107], v206 offset:35840
	ds_read_b128 v[124:127], v206 offset:49152
	ds_read_b128 v[128:131], v206 offset:50176
	ds_read_b128 v[132:135], v206 offset:51200
	ds_read_b128 v[136:139], v206 offset:52224
	s_add_u32 s34, s34, 0x40000
	s_addc_u32 s35, s35, 0
	s_mov_b32 m0, s33
	ds_read_b128 v[160:163], v245 offset:32768
	ds_read_b128 v[164:167], v245 offset:33792
	ds_read_b128 v[182:185], v245 offset:34816
	ds_read_b128 v[186:189], v245 offset:35840
	ds_read_b128 v[190:193], v245 offset:36864
	ds_read_b128 v[194:197], v245 offset:37888
	ds_read_b128 v[198:201], v245 offset:38912
	ds_read_b128 v[202:205], v245 offset:39936
	global_load_lds_dwordx4 v174, s[34:35]
	s_mov_b32 m0, s78
	s_nop 0
	global_load_lds_dwordx4 v176, s[34:35]
	s_waitcnt vmcnt(8)
	s_waitcnt lgkmcnt(0)
	s_barrier
; #define PG8_STAGE(bufoff, gbase, voff) do { _Pragma("unroll") for (int _i = 0; _i < 2; ++_i) \
;         __builtin_amdgcn_global_load_lds((const unsigned*)((const char*)(gbase) + (voff)[_i]), (LAS unsigned*)(lds + (bufoff) + ldsw + _i * 8192), 16, 0, 0); } while (0)
; #define PG8_LDA(dst, b, h) do { _Pragma("unroll") for (int m = 0; m < 4; ++m) _Pragma("unroll") for (int k = 0; k < 2; ++k) dst[m][k] = *(const LAS bf16x8*)(lds + PG8_SA(b, h) + aoff + m * 2048 + k * 1024); } while (0)
; #define PG8_MMA(ai, bj, At, Bt) do { __builtin_amdgcn_s_setprio(1); _Pragma("unroll") for (int m = 0; m < 4; ++m) _Pragma("unroll") for (int n = 0; n < 2; ++n) _Pragma("unroll") for (int k = 0; k < 2; ++k) \
;         acc[ai][bj][m][n] = __builtin_amdgcn_mfma_f32_16x16x32_bf16(Bt[n][k], At[m][k], acc[ai][bj][m][n], 0, 0, 0); __builtin_amdgcn_s_setprio(0); } while (0)
; #define PG8_WAIT_V(n) asm volatile("s_waitcnt vmcnt(" #n ")" ::: "memory")
; #define PG8_WAIT_L(n) asm volatile("s_waitcnt lgkmcnt(" #n ")" ::: "memory")
; #define PG8_BAR __builtin_amdgcn_s_barrier()
; #define PG8_SCHED __builtin_amdgcn_sched_barrier(0)
; template <class Epi, class Sched, bool ALIGN_EPI>
; DI void gemm_phase(LAS unsigned char* lds, const Gemm g, const Sched& S, const Epi& E) {
;     ...
;             PG8_WAIT_V(8); PG8_WAIT_L(0); PG8_BAR; PG8_MMA(0, 0, At, B0); PG8_MMA(0, 1, At, B1); PG8_BAR; PG8_SCHED;
;             PG8_LDA(At, 1, 1); PG8_STAGE(PG8_SB(1, 0), b3, voffA); PG8_STAGE(PG8_SB(1, 1), b3 + hstep, voffA); PG8_STAGE(PG8_SA(1, 0), a3, voffA);
;             PG8_WAIT_V(8); PG8_WAIT_L(0); PG8_BAR; PG8_MMA(1, 0, At, B0); PG8_MMA(1, 1, At, B1); PG8_BAR; PG8_SCHED;
;         }
;         if constexpr (ALIGN_EPI) { if (wr == 0) PG8_BAR; }
	s_setprio 1
	s_waitcnt lgkmcnt(0)
	v_mfma_f32_16x16x32_bf16 v[156:159], v[84:87], v[160:163], v[156:159]
	v_mfma_f32_16x16x32_bf16 v[76:79], v[96:99], v[160:163], v[76:79]
	v_mfma_f32_16x16x32_bf16 v[148:151], v[84:87], v[182:185], v[148:151]
	v_mfma_f32_16x16x32_bf16 v[68:71], v[96:99], v[182:185], v[68:71]
	v_mfma_f32_16x16x32_bf16 v[140:143], v[84:87], v[190:193], v[140:143]
	v_mfma_f32_16x16x32_bf16 v[60:63], v[96:99], v[190:193], v[60:63]
	v_mfma_f32_16x16x32_bf16 v[116:119], v[84:87], v[198:201], v[116:119]
	v_mfma_f32_16x16x32_bf16 v[36:39], v[96:99], v[198:201], v[36:39]
	v_mfma_f32_16x16x32_bf16 v[156:159], v[88:91], v[164:167], v[156:159]
	v_mfma_f32_16x16x32_bf16 v[76:79], v[104:107], v[164:167], v[76:79]
	v_mfma_f32_16x16x32_bf16 v[148:151], v[88:91], v[186:189], v[148:151]
	v_mfma_f32_16x16x32_bf16 v[68:71], v[104:107], v[186:189], v[68:71]
	v_mfma_f32_16x16x32_bf16 v[140:143], v[88:91], v[194:197], v[140:143]
	v_mfma_f32_16x16x32_bf16 v[60:63], v[104:107], v[194:197], v[60:63]
	v_mfma_f32_16x16x32_bf16 v[116:119], v[88:91], v[202:205], v[116:119]
	v_mfma_f32_16x16x32_bf16 v[36:39], v[104:107], v[202:205], v[36:39]
	s_setprio 0
	s_setprio 1
	v_mfma_f32_16x16x32_bf16 v[152:155], v[124:127], v[160:163], v[152:155]
	v_mfma_f32_16x16x32_bf16 v[72:75], v[132:135], v[160:163], v[72:75]
	v_mfma_f32_16x16x32_bf16 v[144:147], v[124:127], v[182:185], v[144:147]
	v_mfma_f32_16x16x32_bf16 v[64:67], v[132:135], v[182:185], v[64:67]
	v_mfma_f32_16x16x32_bf16 v[120:123], v[124:127], v[190:193], v[120:123]
	v_mfma_f32_16x16x32_bf16 v[40:43], v[132:135], v[190:193], v[40:43]
	v_mfma_f32_16x16x32_bf16 v[112:115], v[124:127], v[198:201], v[112:115]
	v_mfma_f32_16x16x32_bf16 v[32:35], v[132:135], v[198:201], v[32:35]
	v_mfma_f32_16x16x32_bf16 v[152:155], v[128:131], v[164:167], v[152:155]
	v_mfma_f32_16x16x32_bf16 v[72:75], v[136:139], v[164:167], v[72:75]
	v_mfma_f32_16x16x32_bf16 v[144:147], v[128:131], v[186:189], v[144:147]
	v_mfma_f32_16x16x32_bf16 v[64:67], v[136:139], v[186:189], v[64:67]
	v_mfma_f32_16x16x32_bf16 v[120:123], v[128:131], v[194:197], v[120:123]
	v_mfma_f32_16x16x32_bf16 v[40:43], v[136:139], v[194:197], v[40:43]
	v_mfma_f32_16x16x32_bf16 v[112:115], v[128:131], v[202:205], v[112:115]
	v_mfma_f32_16x16x32_bf16 v[32:35], v[136:139], v[202:205], v[32:35]
	s_setprio 0
	s_barrier
	s_add_i32 s34, s46, s92
	s_mov_b32 m0, s34
	ds_read_b128 v[160:163], v245 offset:49152
	ds_read_b128 v[164:167], v245 offset:50176
	ds_read_b128 v[182:185], v245 offset:51200
	ds_read_b128 v[186:189], v245 offset:52224
	ds_read_b128 v[190:193], v245 offset:53248
	ds_read_b128 v[194:197], v245 offset:54272
	ds_read_b128 v[198:201], v245 offset:55296
	ds_read_b128 v[202:205], v245 offset:56320
	global_load_lds_dwordx4 v174, s[94:95]
	s_add_i32 m0, s34, 0x2000
	s_add_u32 s30, s30, 0x40080
	s_addc_u32 s31, s31, 0
	s_add_i32 s34, s47, s92
	global_load_lds_dwordx4 v176, s[94:95]
	s_mov_b32 m0, s34
	s_nop 0
	global_load_lds_dwordx4 v174, s[30:31]
	s_add_i32 m0, s34, 0x2000
	s_nop 0
	global_load_lds_dwordx4 v176, s[30:31]
	s_mov_b32 m0, s8
	s_nop 0
	global_load_lds_dwordx4 v174, s[96:97]
	s_mov_b32 m0, s9
	s_nop 0
	global_load_lds_dwordx4 v176, s[96:97]
	s_waitcnt vmcnt(8)
	s_waitcnt lgkmcnt(0)
	s_barrier
	s_setprio 1
	s_waitcnt lgkmcnt(0)
	v_mfma_f32_16x16x32_bf16 v[108:111], v[84:87], v[160:163], v[108:111]
	v_mfma_f32_16x16x32_bf16 v[28:31], v[96:99], v[160:163], v[28:31]
	v_mfma_f32_16x16x32_bf16 v[100:103], v[84:87], v[182:185], v[100:103]
	v_mfma_f32_16x16x32_bf16 v[20:23], v[96:99], v[182:185], v[20:23]
	v_mfma_f32_16x16x32_bf16 v[92:95], v[84:87], v[190:193], v[92:95]
	v_mfma_f32_16x16x32_bf16 v[12:15], v[96:99], v[190:193], v[12:15]
	v_mfma_f32_16x16x32_bf16 v[44:47], v[84:87], v[198:201], v[44:47]
	v_mfma_f32_16x16x32_bf16 v[4:7], v[96:99], v[198:201], v[4:7]
	v_mfma_f32_16x16x32_bf16 v[108:111], v[88:91], v[164:167], v[108:111]
	v_mfma_f32_16x16x32_bf16 v[28:31], v[104:107], v[164:167], v[28:31]
	v_mfma_f32_16x16x32_bf16 v[100:103], v[88:91], v[186:189], v[100:103]
	v_mfma_f32_16x16x32_bf16 v[20:23], v[104:107], v[186:189], v[20:23]
	v_mfma_f32_16x16x32_bf16 v[92:95], v[88:91], v[194:197], v[92:95]
	v_mfma_f32_16x16x32_bf16 v[12:15], v[104:107], v[194:197], v[12:15]
	v_mfma_f32_16x16x32_bf16 v[84:87], v[88:91], v[202:205], v[44:47]
	v_mfma_f32_16x16x32_bf16 v[4:7], v[104:107], v[202:205], v[4:7]
	s_setprio 0
	s_setprio 1
	v_mfma_f32_16x16x32_bf16 v[44:47], v[124:127], v[160:163], v[48:51]
	v_mfma_f32_16x16x32_bf16 v[104:107], v[128:131], v[164:167], v[44:47]
	v_mfma_f32_16x16x32_bf16 v[44:47], v[124:127], v[182:185], v[52:55]
	v_mfma_f32_16x16x32_bf16 v[96:99], v[128:131], v[186:189], v[44:47]
	v_mfma_f32_16x16x32_bf16 v[44:47], v[124:127], v[190:193], v[56:59]
	v_mfma_f32_16x16x32_bf16 v[24:27], v[132:135], v[160:163], v[24:27]
	v_mfma_f32_16x16x32_bf16 v[16:19], v[132:135], v[182:185], v[16:19]
	v_mfma_f32_16x16x32_bf16 v[88:91], v[128:131], v[194:197], v[44:47]
	v_mfma_f32_16x16x32_bf16 v[8:11], v[132:135], v[190:193], v[8:11]
	v_mfma_f32_16x16x32_bf16 v[44:47], v[124:127], v[198:201], v[80:83]
	v_mfma_f32_16x16x32_bf16 v[0:3], v[132:135], v[198:201], v[0:3]
	v_mfma_f32_16x16x32_bf16 v[24:27], v[136:139], v[164:167], v[24:27]
	v_mfma_f32_16x16x32_bf16 v[16:19], v[136:139], v[186:189], v[16:19]
	v_mfma_f32_16x16x32_bf16 v[8:11], v[136:139], v[194:197], v[8:11]
	v_mfma_f32_16x16x32_bf16 v[80:83], v[128:131], v[202:205], v[44:47]
	v_mfma_f32_16x16x32_bf16 v[0:3], v[136:139], v[202:205], v[0:3]
	s_setprio 0
	s_barrier
	s_add_i32 s45, s45, 2
	s_add_u32 s0, s0, 0x100
	s_addc_u32 s1, s1, 0
	s_add_u32 s43, s43, 0x100
	s_addc_u32 s44, s44, 0
	s_cmp_gt_u32 s45, 13
	s_cbranch_scc0 .LBB0_826
	s_and_b64 vcc, exec, s[18:19]
	s_cbranch_vccz .LBB0_829
	s_barrier
